# adds: G1 tile-order arithmetic uses gsz=8 shift/mask (no float-rcp division); trailing half restore barrier moved after next-unit arithmetic
# speedup vs baseline: 1.0300x; 1.0044x over previous
.LBB0_65:
	s_add_i32 s50, s50, 1
	v_readlane_b32 s13, v254, 3
	s_mul_i32 s13, s50, s13
	s_mul_hi_u32 s15, s50, s54
	s_add_i32 s15, s15, s13
	s_mul_i32 s13, s50, s54
	s_add_u32 s16, s13, s72
	s_addc_u32 s17, s15, s36
	v_mov_b64_e32 v[0:1], 0x1600
	v_cmp_lt_i64_e64 s[42:43], s[16:17], v[0:1]
	v_mov_b64_e32 v[0:1], 0x15ff
	v_cmp_gt_i64_e32 vcc, s[16:17], v[0:1]
	s_cbranch_vccnz .LBB0_67
	s_ashr_i32 s12, s16, 31
	s_lshr_b32 s12, s12, 29
	s_add_i32 s12, s16, s12
	s_ashr_i32 s13, s12, 3
	s_and_b32 s12, s12, -8
	s_sub_i32 s12, s16, s12
	s_cmp_lt_i32 s12, 0
	s_movk_i32 s14, 0x2c1
	s_cselect_b32 s14, s14, 0x2c0
	s_mul_i32 s12, s12, s14
	s_add_i32 s12, s12, s13
	s_mul_hi_i32 s13, s12, 0x2e8ba2e9
	s_lshr_b32 s14, s13, 31
	s_ashr_i32 s13, s13, 5
	s_add_i32 s13, s13, s14
	s_lshl_b32 s14, s13, 3
	s_mulk_i32 s13, 0xb0
	s_sub_i32 s13, s12, s13
	s_lshr_b32 s12, s13, 3
	s_and_b32 s13, s13, 7
	s_add_i32 s14, s14, s13
.LBB0_67:
	s_ashr_i32 s15, s14, 31
	s_lshl_b64 s[16:17], s[14:15], 19
	s_add_u32 s16, s30, s16
	s_addc_u32 s17, s31, s17
	s_and_b64 s[18:19], s[42:43], exec
	s_cselect_b32 s15, s17, s23
	s_cselect_b32 s21, s16, s22
	s_ashr_i32 s13, s12, 31
	s_lshl_b64 s[18:19], s[12:13], 19
	s_add_u32 s18, s34, s18
	s_addc_u32 s19, s35, s19
	s_and_b64 s[26:27], s[42:43], exec
	s_cselect_b32 s13, s19, s25
	s_cselect_b32 s33, s18, s24
	s_add_u32 s22, s22, 0x40080
	s_addc_u32 s23, s23, 0
	s_add_u32 s55, s24, 0x100
	s_addc_u32 s56, s25, 0
	s_mov_b32 s57, -2
	s_cmp_lt_u32 s50, 2
	s_cbranch_scc1 .Lrb68_skip
	s_andn2_b64 vcc, exec, s[6:7]
	s_cbranch_vccnz .Lrb68_skip
	s_barrier
.Lrb68_skip:
	s_add_u32 s24, s22, 0xfffc0080
	s_addc_u32 s25, s23, -1
	s_add_i32 s60, 0, 0x10000
	s_cmp_eq_u32 s57, 12
	s_cselect_b32 s27, s15, s25
	s_cselect_b32 s26, s21, s24
	s_cselect_b32 s25, s13, s56
	s_cselect_b32 s24, s33, s55
	s_add_i32 s63, 0, 0x14000
	v_add_u32_e32 v154, s60, v172
	v_add_u32_e32 v176, s63, v172
	ds_read_b128 v[130:133], v154
	ds_read_b128 v[146:149], v154 offset:1024
	ds_read_b128 v[150:153], v154 offset:2048
	ds_read_b128 v[154:157], v154 offset:3072
	ds_read_b128 v[158:161], v176
	ds_read_b128 v[162:165], v176 offset:1024
	ds_read_b128 v[168:171], v176 offset:2048
	ds_read_b128 v[176:179], v176 offset:3072
	v_lshl_add_u64 v[208:209], s[22:23], 0, v[142:143]
	s_add_i32 m0, s37, 0xc000
	ds_read_b128 v[180:183], v175
	ds_read_b128 v[184:187], v175 offset:1024
	ds_read_b128 v[188:191], v175 offset:2048
	ds_read_b128 v[192:195], v175 offset:3072
	ds_read_b128 v[196:199], v175 offset:4096
	ds_read_b128 v[200:203], v175 offset:5120
	ds_read_b128 v[204:207], v175 offset:6144
	ds_read_b128 v[216:219], v175 offset:7168
	global_load_lds_dwordx4 v[208:209], off
	v_lshl_add_u64 v[208:209], s[22:23], 0, v[144:145]
	s_add_i32 m0, s37, 0xe000
	s_nop 0
	global_load_lds_dwordx4 v[208:209], off
	s_waitcnt vmcnt(8)
	s_waitcnt lgkmcnt(0)
	s_barrier
	s_setprio 1
	s_waitcnt lgkmcnt(0)
	v_mfma_f32_16x16x32_f16 v[126:129], v[130:133], v[180:183], 0
	v_mfma_f32_16x16x32_f16 v[118:121], v[150:153], v[180:183], 0
	v_mfma_f32_16x16x32_f16 v[110:113], v[130:133], v[188:191], 0
	v_mfma_f32_16x16x32_f16 v[102:105], v[150:153], v[188:191], 0
	v_mfma_f32_16x16x32_f16 v[92:95], v[130:133], v[196:199], 0
	v_mfma_f32_16x16x32_f16 v[84:87], v[150:153], v[196:199], 0
	v_mfma_f32_16x16x32_f16 v[76:79], v[130:133], v[204:207], 0
	v_mfma_f32_16x16x32_f16 v[68:71], v[150:153], v[204:207], 0
	v_mfma_f32_16x16x32_f16 v[126:129], v[146:149], v[184:187], v[126:129]
	v_mfma_f32_16x16x32_f16 v[118:121], v[154:157], v[184:187], v[118:121]
	v_mfma_f32_16x16x32_f16 v[110:113], v[146:149], v[192:195], v[110:113]
	v_mfma_f32_16x16x32_f16 v[102:105], v[154:157], v[192:195], v[102:105]
	v_mfma_f32_16x16x32_f16 v[92:95], v[146:149], v[200:203], v[92:95]
	v_mfma_f32_16x16x32_f16 v[84:87], v[154:157], v[200:203], v[84:87]
	v_mfma_f32_16x16x32_f16 v[76:79], v[146:149], v[216:219], v[76:79]
	v_mfma_f32_16x16x32_f16 v[68:71], v[154:157], v[216:219], v[68:71]
	v_mfma_f32_16x16x32_f16 v[122:125], v[158:161], v[180:183], 0
	v_mfma_f32_16x16x32_f16 v[114:117], v[168:171], v[180:183], 0
	v_mfma_f32_16x16x32_f16 v[106:109], v[158:161], v[188:191], 0
	v_mfma_f32_16x16x32_f16 v[98:101], v[168:171], v[188:191], 0
	v_mfma_f32_16x16x32_f16 v[88:91], v[158:161], v[196:199], 0
	v_mfma_f32_16x16x32_f16 v[80:83], v[168:171], v[196:199], 0
	v_mfma_f32_16x16x32_f16 v[72:75], v[158:161], v[204:207], 0
	v_mfma_f32_16x16x32_f16 v[64:67], v[168:171], v[204:207], 0
	v_mfma_f32_16x16x32_f16 v[122:125], v[162:165], v[184:187], v[122:125]
	v_mfma_f32_16x16x32_f16 v[114:117], v[176:179], v[184:187], v[114:117]
	v_mfma_f32_16x16x32_f16 v[106:109], v[162:165], v[192:195], v[106:109]
	v_mfma_f32_16x16x32_f16 v[98:101], v[176:179], v[192:195], v[98:101]
	v_mfma_f32_16x16x32_f16 v[88:91], v[162:165], v[200:203], v[88:91]
	v_mfma_f32_16x16x32_f16 v[80:83], v[176:179], v[200:203], v[80:83]
	v_mfma_f32_16x16x32_f16 v[72:75], v[162:165], v[216:219], v[72:75]
	v_mfma_f32_16x16x32_f16 v[64:67], v[176:179], v[216:219], v[64:67]
	s_setprio 0
	s_barrier
	s_add_i32 s60, s60, s29
	v_lshl_add_u64 v[208:209], s[24:25], 0, v[96:97]
	s_mov_b32 m0, s60
	ds_read_b128 v[180:183], v175 offset:16384
	ds_read_b128 v[184:187], v175 offset:17408
	ds_read_b128 v[188:191], v175 offset:18432
	ds_read_b128 v[192:195], v175 offset:19456
	ds_read_b128 v[196:199], v175 offset:20480
	ds_read_b128 v[200:203], v175 offset:21504
	ds_read_b128 v[204:207], v175 offset:22528
	ds_read_b128 v[216:219], v175 offset:23552
	global_load_lds_dwordx4 v[208:209], off
	s_add_i32 m0, s60, 0x2000
	s_add_u32 s60, s24, 0x40000
	v_lshl_add_u64 v[210:211], s[24:25], 0, v[134:135]
	s_addc_u32 s61, s25, 0
	s_add_i32 s63, s63, s29
	global_load_lds_dwordx4 v[210:211], off
	v_lshl_add_u64 v[212:213], s[60:61], 0, v[96:97]
	s_mov_b32 m0, s63
	v_lshl_add_u64 v[220:221], s[26:27], 0, v[136:137]
	global_load_lds_dwordx4 v[212:213], off
	v_lshl_add_u64 v[212:213], s[60:61], 0, v[134:135]
	s_add_i32 m0, s63, 0x2000
	s_nop 0
	global_load_lds_dwordx4 v[212:213], off
	v_lshl_add_u64 v[212:213], s[26:27], 0, v[138:139]
	s_mov_b32 m0, s37
	s_nop 0
	global_load_lds_dwordx4 v[212:213], off
	s_mov_b32 m0, s45
	s_nop 0
	global_load_lds_dwordx4 v[220:221], off
	s_waitcnt vmcnt(8)
	s_waitcnt lgkmcnt(0)
	s_barrier
	s_setprio 1
	s_waitcnt lgkmcnt(0)
	v_mfma_f32_16x16x32_f16 v[60:63], v[130:133], v[180:183], 0
	v_mfma_f32_16x16x32_f16 v[52:55], v[150:153], v[180:183], 0
	v_mfma_f32_16x16x32_f16 v[44:47], v[130:133], v[188:191], 0
	v_mfma_f32_16x16x32_f16 v[36:39], v[150:153], v[188:191], 0
	v_mfma_f32_16x16x32_f16 v[28:31], v[130:133], v[196:199], 0
	v_mfma_f32_16x16x32_f16 v[20:23], v[150:153], v[196:199], 0
	v_mfma_f32_16x16x32_f16 v[12:15], v[130:133], v[204:207], 0
	v_mfma_f32_16x16x32_f16 v[4:7], v[150:153], v[204:207], 0
	v_mfma_f32_16x16x32_f16 v[60:63], v[146:149], v[184:187], v[60:63]
	v_mfma_f32_16x16x32_f16 v[52:55], v[154:157], v[184:187], v[52:55]
	v_mfma_f32_16x16x32_f16 v[44:47], v[146:149], v[192:195], v[44:47]
	v_mfma_f32_16x16x32_f16 v[36:39], v[154:157], v[192:195], v[36:39]
	v_mfma_f32_16x16x32_f16 v[28:31], v[146:149], v[200:203], v[28:31]
	v_mfma_f32_16x16x32_f16 v[20:23], v[154:157], v[200:203], v[20:23]
	v_mfma_f32_16x16x32_f16 v[12:15], v[146:149], v[216:219], v[12:15]
	v_mfma_f32_16x16x32_f16 v[4:7], v[154:157], v[216:219], v[4:7]
	v_mfma_f32_16x16x32_f16 v[56:59], v[158:161], v[180:183], 0
	v_mfma_f32_16x16x32_f16 v[48:51], v[168:171], v[180:183], 0
	v_mfma_f32_16x16x32_f16 v[40:43], v[158:161], v[188:191], 0
	v_mfma_f32_16x16x32_f16 v[32:35], v[168:171], v[188:191], 0
	v_mfma_f32_16x16x32_f16 v[24:27], v[158:161], v[196:199], 0
	v_mfma_f32_16x16x32_f16 v[16:19], v[168:171], v[196:199], 0
	v_mfma_f32_16x16x32_f16 v[8:11], v[158:161], v[204:207], 0
	v_mfma_f32_16x16x32_f16 v[0:3], v[168:171], v[204:207], 0
	v_mfma_f32_16x16x32_f16 v[56:59], v[162:165], v[184:187], v[56:59]
	v_mfma_f32_16x16x32_f16 v[48:51], v[176:179], v[184:187], v[48:51]
	v_mfma_f32_16x16x32_f16 v[40:43], v[162:165], v[192:195], v[40:43]
	v_mfma_f32_16x16x32_f16 v[32:35], v[176:179], v[192:195], v[32:35]
	v_mfma_f32_16x16x32_f16 v[24:27], v[162:165], v[200:203], v[24:27]
	v_mfma_f32_16x16x32_f16 v[16:19], v[176:179], v[200:203], v[16:19]
	v_mfma_f32_16x16x32_f16 v[8:11], v[162:165], v[216:219], v[8:11]
	v_mfma_f32_16x16x32_f16 v[0:3], v[176:179], v[216:219], v[0:3]
	s_setprio 0
	s_barrier
	s_add_i32 s60, 0, 0x18000
	s_add_i32 s61, 0, 0x1c000
	v_add_u32_e32 v154, s60, v172
	v_add_u32_e32 v176, s61, v172
	ds_read_b128 v[130:133], v154
	ds_read_b128 v[146:149], v154 offset:1024
	ds_read_b128 v[150:153], v154 offset:2048
	ds_read_b128 v[154:157], v154 offset:3072
	ds_read_b128 v[158:161], v176
	ds_read_b128 v[162:165], v176 offset:1024
	ds_read_b128 v[168:171], v176 offset:2048
	ds_read_b128 v[176:179], v176 offset:3072
	s_add_u32 s26, s26, 0x40000
	s_addc_u32 s27, s27, 0
	s_mov_b32 m0, s46
	v_lshl_add_u64 v[222:223], s[26:27], 0, v[138:139]
	ds_read_b128 v[180:183], v175 offset:32768
	ds_read_b128 v[184:187], v175 offset:33792
	ds_read_b128 v[188:191], v175 offset:34816
	ds_read_b128 v[192:195], v175 offset:35840
	ds_read_b128 v[196:199], v175 offset:36864
	ds_read_b128 v[200:203], v175 offset:37888
	ds_read_b128 v[204:207], v175 offset:38912
	ds_read_b128 v[216:219], v175 offset:39936
	global_load_lds_dwordx4 v[222:223], off
	v_lshl_add_u64 v[222:223], s[26:27], 0, v[136:137]
	s_mov_b32 m0, s47
	s_nop 0
	global_load_lds_dwordx4 v[222:223], off
	s_waitcnt vmcnt(8)
	s_waitcnt lgkmcnt(0)
	s_barrier
	s_setprio 1
	s_waitcnt lgkmcnt(0)
	v_mfma_f32_16x16x32_f16 v[126:129], v[130:133], v[180:183], v[126:129]
	v_mfma_f32_16x16x32_f16 v[118:121], v[150:153], v[180:183], v[118:121]
	v_mfma_f32_16x16x32_f16 v[110:113], v[130:133], v[188:191], v[110:113]
	v_mfma_f32_16x16x32_f16 v[102:105], v[150:153], v[188:191], v[102:105]
	v_mfma_f32_16x16x32_f16 v[92:95], v[130:133], v[196:199], v[92:95]
	v_mfma_f32_16x16x32_f16 v[84:87], v[150:153], v[196:199], v[84:87]
	v_mfma_f32_16x16x32_f16 v[76:79], v[130:133], v[204:207], v[76:79]
	v_mfma_f32_16x16x32_f16 v[68:71], v[150:153], v[204:207], v[68:71]
	v_mfma_f32_16x16x32_f16 v[126:129], v[146:149], v[184:187], v[126:129]
	v_mfma_f32_16x16x32_f16 v[118:121], v[154:157], v[184:187], v[118:121]
	v_mfma_f32_16x16x32_f16 v[110:113], v[146:149], v[192:195], v[110:113]
	v_mfma_f32_16x16x32_f16 v[102:105], v[154:157], v[192:195], v[102:105]
	v_mfma_f32_16x16x32_f16 v[92:95], v[146:149], v[200:203], v[92:95]
	v_mfma_f32_16x16x32_f16 v[84:87], v[154:157], v[200:203], v[84:87]
	v_mfma_f32_16x16x32_f16 v[76:79], v[146:149], v[216:219], v[76:79]
	v_mfma_f32_16x16x32_f16 v[68:71], v[154:157], v[216:219], v[68:71]
	v_mfma_f32_16x16x32_f16 v[122:125], v[158:161], v[180:183], v[122:125]
	v_mfma_f32_16x16x32_f16 v[114:117], v[168:171], v[180:183], v[114:117]
	v_mfma_f32_16x16x32_f16 v[106:109], v[158:161], v[188:191], v[106:109]
	v_mfma_f32_16x16x32_f16 v[98:101], v[168:171], v[188:191], v[98:101]
	v_mfma_f32_16x16x32_f16 v[88:91], v[158:161], v[196:199], v[88:91]
	v_mfma_f32_16x16x32_f16 v[80:83], v[168:171], v[196:199], v[80:83]
	v_mfma_f32_16x16x32_f16 v[72:75], v[158:161], v[204:207], v[72:75]
	v_mfma_f32_16x16x32_f16 v[64:67], v[168:171], v[204:207], v[64:67]
	v_mfma_f32_16x16x32_f16 v[122:125], v[162:165], v[184:187], v[122:125]
	v_mfma_f32_16x16x32_f16 v[114:117], v[176:179], v[184:187], v[114:117]
	v_mfma_f32_16x16x32_f16 v[106:109], v[162:165], v[192:195], v[106:109]
	v_mfma_f32_16x16x32_f16 v[98:101], v[176:179], v[192:195], v[98:101]
	v_mfma_f32_16x16x32_f16 v[88:91], v[162:165], v[200:203], v[88:91]
	v_mfma_f32_16x16x32_f16 v[80:83], v[176:179], v[200:203], v[80:83]
	v_mfma_f32_16x16x32_f16 v[72:75], v[162:165], v[216:219], v[72:75]
	v_mfma_f32_16x16x32_f16 v[64:67], v[176:179], v[216:219], v[64:67]
	s_setprio 0
	s_barrier
	s_add_i32 s26, s60, s29
	v_lshl_add_u64 v[208:209], v[208:209], 0, s[94:95]
	s_mov_b32 m0, s26
	ds_read_b128 v[180:183], v175 offset:49152
	ds_read_b128 v[184:187], v175 offset:50176
	ds_read_b128 v[188:191], v175 offset:51200
	ds_read_b128 v[192:195], v175 offset:52224
	ds_read_b128 v[196:199], v175 offset:53248
	ds_read_b128 v[200:203], v175 offset:54272
	ds_read_b128 v[204:207], v175 offset:55296
	ds_read_b128 v[216:219], v175 offset:56320
	global_load_lds_dwordx4 v[208:209], off
	s_add_i32 m0, s26, 0x2000
	s_add_u32 s24, s24, 0x40080
	v_lshl_add_u64 v[208:209], v[210:211], 0, s[94:95]
	s_addc_u32 s25, s25, 0
	s_add_i32 s26, s61, s29
	global_load_lds_dwordx4 v[208:209], off
	v_lshl_add_u64 v[208:209], s[24:25], 0, v[96:97]
	s_mov_b32 m0, s26
	s_nop 0
	global_load_lds_dwordx4 v[208:209], off
	v_lshl_add_u64 v[208:209], s[24:25], 0, v[134:135]
	s_add_i32 m0, s26, 0x2000
	s_nop 0
	global_load_lds_dwordx4 v[208:209], off
	v_lshl_add_u64 v[208:209], v[212:213], 0, s[94:95]
	s_mov_b32 m0, s48
	s_nop 0
	global_load_lds_dwordx4 v[208:209], off
	v_lshl_add_u64 v[208:209], v[220:221], 0, s[94:95]
	s_mov_b32 m0, s49
	s_nop 0
	global_load_lds_dwordx4 v[208:209], off
	s_waitcnt vmcnt(8)
	s_waitcnt lgkmcnt(0)
	s_barrier
	s_setprio 1
	s_waitcnt lgkmcnt(0)
	v_mfma_f32_16x16x32_f16 v[60:63], v[130:133], v[180:183], v[60:63]
	v_mfma_f32_16x16x32_f16 v[52:55], v[150:153], v[180:183], v[52:55]
	v_mfma_f32_16x16x32_f16 v[44:47], v[130:133], v[188:191], v[44:47]
	v_mfma_f32_16x16x32_f16 v[36:39], v[150:153], v[188:191], v[36:39]
	v_mfma_f32_16x16x32_f16 v[28:31], v[130:133], v[196:199], v[28:31]
	v_mfma_f32_16x16x32_f16 v[20:23], v[150:153], v[196:199], v[20:23]
	v_mfma_f32_16x16x32_f16 v[12:15], v[130:133], v[204:207], v[12:15]
	v_mfma_f32_16x16x32_f16 v[4:7], v[150:153], v[204:207], v[4:7]
	v_mfma_f32_16x16x32_f16 v[60:63], v[146:149], v[184:187], v[60:63]
	v_mfma_f32_16x16x32_f16 v[52:55], v[154:157], v[184:187], v[52:55]
	v_mfma_f32_16x16x32_f16 v[44:47], v[146:149], v[192:195], v[44:47]
	v_mfma_f32_16x16x32_f16 v[36:39], v[154:157], v[192:195], v[36:39]
	v_mfma_f32_16x16x32_f16 v[28:31], v[146:149], v[200:203], v[28:31]
	v_mfma_f32_16x16x32_f16 v[20:23], v[154:157], v[200:203], v[20:23]
	v_mfma_f32_16x16x32_f16 v[12:15], v[146:149], v[216:219], v[12:15]
	v_mfma_f32_16x16x32_f16 v[4:7], v[154:157], v[216:219], v[4:7]
	v_mfma_f32_16x16x32_f16 v[56:59], v[158:161], v[180:183], v[56:59]
	v_mfma_f32_16x16x32_f16 v[48:51], v[168:171], v[180:183], v[48:51]
	v_mfma_f32_16x16x32_f16 v[40:43], v[158:161], v[188:191], v[40:43]
	v_mfma_f32_16x16x32_f16 v[32:35], v[168:171], v[188:191], v[32:35]
	v_mfma_f32_16x16x32_f16 v[24:27], v[158:161], v[196:199], v[24:27]
	v_mfma_f32_16x16x32_f16 v[16:19], v[168:171], v[196:199], v[16:19]
	v_mfma_f32_16x16x32_f16 v[8:11], v[158:161], v[204:207], v[8:11]
	v_mfma_f32_16x16x32_f16 v[0:3], v[168:171], v[204:207], v[0:3]
	v_mfma_f32_16x16x32_f16 v[56:59], v[162:165], v[184:187], v[56:59]
	v_mfma_f32_16x16x32_f16 v[48:51], v[176:179], v[184:187], v[48:51]
	v_mfma_f32_16x16x32_f16 v[40:43], v[162:165], v[192:195], v[40:43]
	v_mfma_f32_16x16x32_f16 v[32:35], v[176:179], v[192:195], v[32:35]
	v_mfma_f32_16x16x32_f16 v[24:27], v[162:165], v[200:203], v[24:27]
	v_mfma_f32_16x16x32_f16 v[16:19], v[176:179], v[200:203], v[16:19]
	v_mfma_f32_16x16x32_f16 v[8:11], v[162:165], v[216:219], v[8:11]
	v_mfma_f32_16x16x32_f16 v[0:3], v[176:179], v[216:219], v[0:3]
	s_setprio 0
	s_barrier
	s_add_i32 s57, s57, 2
	s_add_u32 s22, s22, 0x100
	s_addc_u32 s23, s23, 0
	s_add_u32 s55, s55, 0x100
	s_addc_u32 s56, s56, 0
	s_cmp_gt_u32 s57, 13
	s_cbranch_scc0 .LBB0_68
	s_branch .Lz68_exit

.LBB0_78:
	s_waitcnt lgkmcnt(0)
	v_mul_f32_e32 v132, 0xbfb8aa3b, v170
	v_mul_f32_e32 v133, v170, v170
	v_mul_f32_e32 v122, v126, v122
	v_mul_f32_e32 v126, v126, v132
	v_rcp_f32_e32 v133, v133
	v_exp_f32_e32 v126, v126
	v_mul_f32_e32 v123, v127, v123
	v_mul_f32_e32 v114, v118, v114
	v_mul_f32_e32 v118, v118, v132
	v_fma_f32 v126, v126, v133, v133
	v_rcp_f32_e32 v126, v126
	v_exp_f32_e32 v118, v118
	v_mul_f32_e32 v115, v119, v115
	v_lshl_or_b32 v130, s2, 7, v173
	v_mul_f32_e32 v122, v122, v126
	v_mul_f32_e32 v126, v127, v132
	v_exp_f32_e32 v126, v126
	v_fma_f32 v118, v118, v133, v133
	v_rcp_f32_e32 v118, v118
	v_ashrrev_i32_e32 v131, 31, v130
	v_fma_f32 v126, v126, v133, v133
	v_rcp_f32_e32 v126, v126
	v_mul_f32_e32 v114, v114, v118
	v_mul_f32_e32 v118, v119, v132
	v_exp_f32_e32 v118, v118
	v_mul_f32_e32 v123, v123, v126
	v_cvt_pk_bf16_f32 v122, v122, v123
	v_mul_f32_e32 v123, v128, v124
	v_mul_f32_e32 v124, v128, v132
	v_exp_f32_e32 v124, v124
	v_fma_f32 v118, v118, v133, v133
	v_rcp_f32_e32 v118, v118
	v_mul_f32_e32 v106, v110, v106
	v_fma_f32 v124, v124, v133, v133
	v_rcp_f32_e32 v124, v124
	v_mul_f32_e32 v115, v115, v118
	v_mul_f32_e32 v107, v111, v107
	v_mul_f32_e32 v98, v102, v98
	v_mul_f32_e32 v123, v123, v124
	v_mul_f32_e32 v124, v129, v125
	v_mul_f32_e32 v125, v129, v132
	v_exp_f32_e32 v125, v125
	v_mul_f32_e32 v99, v103, v99
	v_mul_f32_e32 v88, v92, v88
	v_mul_f32_e32 v89, v93, v89
	v_fma_f32 v125, v125, v133, v133
	v_rcp_f32_e32 v125, v125
	v_mul_f32_e32 v80, v84, v80
	v_mul_f32_e32 v81, v85, v81
	v_mul_f32_e32 v72, v76, v72
	v_mul_f32_e32 v124, v124, v125
	v_cvt_pk_bf16_f32 v123, v123, v124
	v_cvt_pk_bf16_f32 v124, v114, v115
	v_mul_f32_e32 v115, v120, v132
	v_mul_f32_e32 v114, v120, v116
	v_exp_f32_e32 v115, v115
	v_mul_f32_e32 v116, v121, v132
	v_exp_f32_e32 v116, v116
	v_mul_f32_e32 v73, v77, v73
	v_fma_f32 v115, v115, v133, v133
	v_rcp_f32_e32 v115, v115
	v_fmac_f32_e32 v133, v116, v133
	v_rcp_f32_e32 v116, v133
	v_mul_f32_e32 v64, v68, v64
	v_mul_f32_e32 v114, v114, v115
	v_mul_f32_e32 v115, v121, v117
	v_mul_f32_e32 v115, v115, v116
	v_cvt_pk_bf16_f32 v125, v114, v115
	v_mov_b64_e32 v[114:115], s[8:9]
	v_mad_u64_u32 v[118:119], s[20:21], v168, s65, v[114:115]
	v_mov_b32_e32 v116, v119
	v_mad_u64_u32 v[116:117], s[20:21], v169, s65, v[116:117]
	v_mov_b32_e32 v119, v116
	v_lshlrev_b64 v[116:117], 1, v[130:131]
	v_lshl_add_u64 v[118:119], v[118:119], 0, v[116:117]
	global_store_dwordx4 v[118:119], v[122:125], off
	v_mul_f32_e32 v118, 0xbfb8aa3b, v171
	v_mul_f32_e32 v119, v171, v171
	v_mul_f32_e32 v110, v110, v118
	v_rcp_f32_e32 v119, v119
	v_exp_f32_e32 v110, v110
	v_mul_f32_e32 v102, v102, v118
	v_exp_f32_e32 v102, v102
	v_mul_f32_e32 v65, v69, v65
	v_fma_f32 v110, v110, v119, v119
	v_rcp_f32_e32 v110, v110
	v_fma_f32 v102, v102, v119, v119
	v_rcp_f32_e32 v102, v102
	v_mul_f32_e32 v56, v60, v56
	v_mul_f32_e32 v106, v106, v110
	v_mul_f32_e32 v110, v111, v118
	v_exp_f32_e32 v110, v110
	v_mul_f32_e32 v98, v98, v102
	v_mul_f32_e32 v102, v103, v118
	v_exp_f32_e32 v102, v102
	v_fma_f32 v110, v110, v119, v119
	v_rcp_f32_e32 v110, v110
	v_mul_f32_e32 v57, v61, v57
	v_fma_f32 v102, v102, v119, v119
	v_rcp_f32_e32 v102, v102
	v_mul_f32_e32 v107, v107, v110
	v_cvt_pk_bf16_f32 v106, v106, v107
	v_mul_f32_e32 v107, v112, v108
	v_mul_f32_e32 v108, v112, v118
	v_exp_f32_e32 v108, v108
	v_mul_f32_e32 v99, v99, v102
	v_mul_f32_e32 v48, v52, v48
	v_mul_f32_e32 v49, v53, v49
	v_fma_f32 v108, v108, v119, v119
	v_rcp_f32_e32 v108, v108
	v_mul_f32_e32 v40, v44, v40
	v_mul_f32_e32 v41, v45, v41
	v_mul_f32_e32 v32, v36, v32
	v_mul_f32_e32 v107, v107, v108
	v_mul_f32_e32 v108, v113, v109
	v_mul_f32_e32 v109, v113, v118
	v_exp_f32_e32 v109, v109
	v_mul_f32_e32 v33, v37, v33
	v_mul_f32_e32 v24, v28, v24
	v_mul_f32_e32 v25, v29, v25
	v_fma_f32 v109, v109, v119, v119
	v_rcp_f32_e32 v109, v109
	v_mul_f32_e32 v16, v20, v16
	v_mul_f32_e32 v17, v21, v17
	v_mul_f32_e32 v8, v12, v8
	v_mul_f32_e32 v108, v108, v109
	v_cvt_pk_bf16_f32 v107, v107, v108
	v_cvt_pk_bf16_f32 v108, v98, v99
	v_mul_f32_e32 v99, v104, v118
	v_mul_f32_e32 v98, v104, v100
	v_exp_f32_e32 v99, v99
	v_mul_f32_e32 v100, v105, v118
	v_exp_f32_e32 v100, v100
	v_mul_f32_e32 v9, v13, v9
	v_fma_f32 v99, v99, v119, v119
	v_rcp_f32_e32 v99, v99
	v_fmac_f32_e32 v119, v100, v119
	v_rcp_f32_e32 v100, v119
	v_mul_f32_e32 v0, v4, v0
	v_mul_f32_e32 v98, v98, v99
	v_mul_f32_e32 v99, v105, v101
	v_mul_f32_e32 v99, v99, v100
	v_cvt_pk_bf16_f32 v109, v98, v99
	v_mad_u64_u32 v[98:99], s[20:21], v164, s65, v[114:115]
	v_mov_b32_e32 v100, v99
	v_mad_u64_u32 v[100:101], s[20:21], v165, s65, v[100:101]
	v_mov_b32_e32 v99, v100
	v_lshl_add_u64 v[98:99], v[98:99], 0, v[116:117]
	global_store_dwordx4 v[98:99], v[106:109], off
	v_mul_f32_e32 v98, 0xbfb8aa3b, v162
	v_mul_f32_e32 v99, v162, v162
	v_mul_f32_e32 v92, v92, v98
	v_rcp_f32_e32 v99, v99
	v_exp_f32_e32 v92, v92
	v_mul_f32_e32 v84, v84, v98
	v_exp_f32_e32 v84, v84
	v_mul_f32_e32 v1, v5, v1
	v_fma_f32 v92, v92, v99, v99
	v_rcp_f32_e32 v92, v92
	v_fma_f32 v84, v84, v99, v99
	v_rcp_f32_e32 v84, v84
	s_andn2_b64 vcc, exec, s[42:43]
	v_mul_f32_e32 v88, v88, v92
	v_mul_f32_e32 v92, v93, v98
	v_exp_f32_e32 v92, v92
	v_mul_f32_e32 v80, v80, v84
	v_mul_f32_e32 v84, v85, v98
	v_exp_f32_e32 v84, v84
	v_fma_f32 v92, v92, v99, v99
	v_rcp_f32_e32 v92, v92
	v_fma_f32 v84, v84, v99, v99
	v_rcp_f32_e32 v84, v84
	v_mul_f32_e32 v89, v89, v92
	v_cvt_pk_bf16_f32 v88, v88, v89
	v_mul_f32_e32 v89, v94, v90
	v_mul_f32_e32 v90, v94, v98
	v_exp_f32_e32 v90, v90
	v_mul_f32_e32 v81, v81, v84
	v_fma_f32 v90, v90, v99, v99
	v_rcp_f32_e32 v90, v90
	s_nop 0
	v_mul_f32_e32 v89, v89, v90
	v_mul_f32_e32 v90, v95, v91
	v_mul_f32_e32 v91, v95, v98
	v_exp_f32_e32 v91, v91
	s_nop 0
	v_fma_f32 v91, v91, v99, v99
	v_rcp_f32_e32 v91, v91
	s_nop 0
	v_mul_f32_e32 v90, v90, v91
	v_cvt_pk_bf16_f32 v89, v89, v90
	v_cvt_pk_bf16_f32 v90, v80, v81
	v_mul_f32_e32 v81, v86, v98
	v_mul_f32_e32 v80, v86, v82
	v_exp_f32_e32 v81, v81
	v_mul_f32_e32 v82, v87, v98
	v_exp_f32_e32 v82, v82
	v_fma_f32 v81, v81, v99, v99
	v_rcp_f32_e32 v81, v81
	v_fmac_f32_e32 v99, v82, v99
	v_rcp_f32_e32 v82, v99
	v_mul_f32_e32 v80, v80, v81
	v_mul_f32_e32 v81, v87, v83
	v_mul_f32_e32 v81, v81, v82
	v_cvt_pk_bf16_f32 v91, v80, v81
	v_mad_u64_u32 v[80:81], s[20:21], v160, s65, v[114:115]
	v_mov_b32_e32 v82, v81
	v_mad_u64_u32 v[82:83], s[20:21], v161, s65, v[82:83]
	v_mov_b32_e32 v81, v82
	v_lshl_add_u64 v[80:81], v[80:81], 0, v[116:117]
	global_store_dwordx4 v[80:81], v[88:91], off
	v_mul_f32_e32 v80, 0xbfb8aa3b, v163
	v_mul_f32_e32 v81, v163, v163
	v_mul_f32_e32 v76, v76, v80
	v_rcp_f32_e32 v81, v81
	v_exp_f32_e32 v76, v76
	v_mul_f32_e32 v68, v68, v80
	v_exp_f32_e32 v68, v68
	v_fma_f32 v76, v76, v81, v81
	v_rcp_f32_e32 v76, v76
	v_fma_f32 v68, v68, v81, v81
	v_rcp_f32_e32 v68, v68
	v_mul_f32_e32 v72, v72, v76
	v_mul_f32_e32 v76, v77, v80
	v_exp_f32_e32 v76, v76
	v_mul_f32_e32 v64, v64, v68
	v_mul_f32_e32 v68, v69, v80
	v_exp_f32_e32 v68, v68
	v_fma_f32 v76, v76, v81, v81
	v_rcp_f32_e32 v76, v76
	v_fma_f32 v68, v68, v81, v81
	v_rcp_f32_e32 v68, v68
	v_mul_f32_e32 v73, v73, v76
	v_cvt_pk_bf16_f32 v72, v72, v73
	v_mul_f32_e32 v73, v78, v74
	v_mul_f32_e32 v74, v78, v80
	v_exp_f32_e32 v74, v74
	v_mul_f32_e32 v65, v65, v68
	v_fma_f32 v74, v74, v81, v81
	v_rcp_f32_e32 v74, v74
	s_nop 0
	v_mul_f32_e32 v73, v73, v74
	v_mul_f32_e32 v74, v79, v75
	v_mul_f32_e32 v75, v79, v80
	v_exp_f32_e32 v75, v75
	s_nop 0
	v_fma_f32 v75, v75, v81, v81
	v_rcp_f32_e32 v75, v75
	s_nop 0
	v_mul_f32_e32 v74, v74, v75
	v_cvt_pk_bf16_f32 v73, v73, v74
	v_cvt_pk_bf16_f32 v74, v64, v65
	v_mul_f32_e32 v65, v70, v80
	v_mul_f32_e32 v64, v70, v66
	v_exp_f32_e32 v65, v65
	v_mul_f32_e32 v66, v71, v80
	v_exp_f32_e32 v66, v66
	v_fma_f32 v65, v65, v81, v81
	v_rcp_f32_e32 v65, v65
	v_fmac_f32_e32 v81, v66, v81
	v_rcp_f32_e32 v66, v81
	v_mul_f32_e32 v64, v64, v65
	v_mul_f32_e32 v65, v71, v67
	v_mul_f32_e32 v65, v65, v66
	v_cvt_pk_bf16_f32 v75, v64, v65
	v_mad_u64_u32 v[64:65], s[20:21], v156, s65, v[114:115]
	v_mov_b32_e32 v66, v65
	v_mad_u64_u32 v[66:67], s[20:21], v157, s65, v[66:67]
	v_mov_b32_e32 v65, v66
	v_lshl_add_u64 v[64:65], v[64:65], 0, v[116:117]
	global_store_dwordx4 v[64:65], v[72:75], off
	v_mul_f32_e32 v64, 0xbfb8aa3b, v158
	v_mul_f32_e32 v65, v158, v158
	v_mul_f32_e32 v60, v60, v64
	v_rcp_f32_e32 v65, v65
	v_exp_f32_e32 v60, v60
	v_mul_f32_e32 v52, v52, v64
	v_exp_f32_e32 v52, v52
	v_fma_f32 v60, v60, v65, v65
	v_rcp_f32_e32 v60, v60
	v_fma_f32 v52, v52, v65, v65
	v_rcp_f32_e32 v52, v52
	v_mul_f32_e32 v56, v56, v60
	v_mul_f32_e32 v60, v61, v64
	v_exp_f32_e32 v60, v60
	v_mul_f32_e32 v48, v48, v52
	v_mul_f32_e32 v52, v53, v64
	v_exp_f32_e32 v52, v52
	v_fma_f32 v60, v60, v65, v65
	v_rcp_f32_e32 v60, v60
	v_fma_f32 v52, v52, v65, v65
	v_rcp_f32_e32 v52, v52
	v_mul_f32_e32 v57, v57, v60
	v_cvt_pk_bf16_f32 v56, v56, v57
	v_mul_f32_e32 v57, v62, v58
	v_mul_f32_e32 v58, v62, v64
	v_exp_f32_e32 v58, v58
	v_mul_f32_e32 v49, v49, v52
	v_fma_f32 v58, v58, v65, v65
	v_rcp_f32_e32 v58, v58
	s_nop 0
	v_mul_f32_e32 v57, v57, v58
	v_mul_f32_e32 v58, v63, v59
	v_mul_f32_e32 v59, v63, v64
	v_exp_f32_e32 v59, v59
	s_nop 0
	v_fma_f32 v59, v59, v65, v65
	v_rcp_f32_e32 v59, v59
	s_nop 0
	v_mul_f32_e32 v58, v58, v59
	v_cvt_pk_bf16_f32 v57, v57, v58
	v_cvt_pk_bf16_f32 v58, v48, v49
	v_mul_f32_e32 v49, v54, v64
	v_mul_f32_e32 v48, v54, v50
	v_exp_f32_e32 v49, v49
	v_mul_f32_e32 v50, v55, v64
	v_exp_f32_e32 v50, v50
	v_fma_f32 v49, v49, v65, v65
	v_rcp_f32_e32 v49, v49
	v_fmac_f32_e32 v65, v50, v65
	v_rcp_f32_e32 v50, v65
	v_mul_f32_e32 v48, v48, v49
	v_mul_f32_e32 v49, v55, v51
	v_mul_f32_e32 v49, v49, v50
	v_cvt_pk_bf16_f32 v59, v48, v49
	v_mad_u64_u32 v[48:49], s[20:21], v154, s65, v[114:115]
	v_mov_b32_e32 v50, v49
	v_mad_u64_u32 v[50:51], s[20:21], v155, s65, v[50:51]
	v_mov_b32_e32 v49, v50
	v_lshl_add_u64 v[48:49], v[48:49], 0, v[116:117]
	global_store_dwordx4 v[48:49], v[56:59], off
	v_mul_f32_e32 v48, 0xbfb8aa3b, v159
	v_mul_f32_e32 v49, v159, v159
	v_mul_f32_e32 v44, v44, v48
	v_rcp_f32_e32 v49, v49
	v_exp_f32_e32 v44, v44
	v_mul_f32_e32 v36, v36, v48
	v_exp_f32_e32 v36, v36
	v_fma_f32 v44, v44, v49, v49
	v_rcp_f32_e32 v44, v44
	v_fma_f32 v36, v36, v49, v49
	v_rcp_f32_e32 v36, v36
	v_mul_f32_e32 v40, v40, v44
	v_mul_f32_e32 v44, v45, v48
	v_exp_f32_e32 v44, v44
	v_mul_f32_e32 v32, v32, v36
	v_mul_f32_e32 v36, v37, v48
	v_exp_f32_e32 v36, v36
	v_fma_f32 v44, v44, v49, v49
	v_rcp_f32_e32 v44, v44
	v_fma_f32 v36, v36, v49, v49
	v_rcp_f32_e32 v36, v36
	v_mul_f32_e32 v41, v41, v44
	v_cvt_pk_bf16_f32 v40, v40, v41
	v_mul_f32_e32 v41, v46, v42
	v_mul_f32_e32 v42, v46, v48
	v_exp_f32_e32 v42, v42
	v_mul_f32_e32 v33, v33, v36
	v_fma_f32 v42, v42, v49, v49
	v_rcp_f32_e32 v42, v42
	s_nop 0
	v_mul_f32_e32 v41, v41, v42
	v_mul_f32_e32 v42, v47, v43
	v_mul_f32_e32 v43, v47, v48
	v_exp_f32_e32 v43, v43
	s_nop 0
	v_fma_f32 v43, v43, v49, v49
	v_rcp_f32_e32 v43, v43
	s_nop 0
	v_mul_f32_e32 v42, v42, v43
	v_cvt_pk_bf16_f32 v41, v41, v42
	v_cvt_pk_bf16_f32 v42, v32, v33
	v_mul_f32_e32 v33, v38, v48
	v_mul_f32_e32 v32, v38, v34
	v_exp_f32_e32 v33, v33
	v_mul_f32_e32 v34, v39, v48
	v_exp_f32_e32 v34, v34
	v_fma_f32 v33, v33, v49, v49
	v_rcp_f32_e32 v33, v33
	v_fmac_f32_e32 v49, v34, v49
	v_rcp_f32_e32 v34, v49
	v_mul_f32_e32 v32, v32, v33
	v_mul_f32_e32 v33, v39, v35
	v_mul_f32_e32 v33, v33, v34
	v_cvt_pk_bf16_f32 v43, v32, v33
	v_mad_u64_u32 v[32:33], s[20:21], v150, s65, v[114:115]
	v_mov_b32_e32 v34, v33
	v_mad_u64_u32 v[34:35], s[20:21], v151, s65, v[34:35]
	v_mov_b32_e32 v33, v34
	v_lshl_add_u64 v[32:33], v[32:33], 0, v[116:117]
	global_store_dwordx4 v[32:33], v[40:43], off
	v_mul_f32_e32 v32, 0xbfb8aa3b, v152
	v_mul_f32_e32 v33, v152, v152
	v_mul_f32_e32 v28, v28, v32
	v_rcp_f32_e32 v33, v33
	v_exp_f32_e32 v28, v28
	v_mul_f32_e32 v20, v20, v32
	v_exp_f32_e32 v20, v20
	v_fma_f32 v28, v28, v33, v33
	v_rcp_f32_e32 v28, v28
	v_fma_f32 v20, v20, v33, v33
	v_rcp_f32_e32 v20, v20
	v_mul_f32_e32 v24, v24, v28
	v_mul_f32_e32 v28, v29, v32
	v_exp_f32_e32 v28, v28
	v_mul_f32_e32 v16, v16, v20
	v_mul_f32_e32 v20, v21, v32
	v_exp_f32_e32 v20, v20
	v_fma_f32 v28, v28, v33, v33
	v_rcp_f32_e32 v28, v28
	v_fma_f32 v20, v20, v33, v33
	v_rcp_f32_e32 v20, v20
	v_mul_f32_e32 v25, v25, v28
	v_cvt_pk_bf16_f32 v24, v24, v25
	v_mul_f32_e32 v25, v30, v26
	v_mul_f32_e32 v26, v30, v32
	v_exp_f32_e32 v26, v26
	v_mul_f32_e32 v17, v17, v20
	v_fma_f32 v26, v26, v33, v33
	v_rcp_f32_e32 v26, v26
	s_nop 0
	v_mul_f32_e32 v25, v25, v26
	v_mul_f32_e32 v26, v31, v27
	v_mul_f32_e32 v27, v31, v32
	v_exp_f32_e32 v27, v27
	s_nop 0
	v_fma_f32 v27, v27, v33, v33
	v_rcp_f32_e32 v27, v27
	s_nop 0
	v_mul_f32_e32 v26, v26, v27
	v_cvt_pk_bf16_f32 v25, v25, v26
	v_cvt_pk_bf16_f32 v26, v16, v17
	v_mul_f32_e32 v17, v22, v32
	v_mul_f32_e32 v16, v22, v18
	v_exp_f32_e32 v17, v17
	v_mul_f32_e32 v18, v23, v32
	v_exp_f32_e32 v18, v18
	v_fma_f32 v17, v17, v33, v33
	v_rcp_f32_e32 v17, v17
	v_fmac_f32_e32 v33, v18, v33
	v_rcp_f32_e32 v18, v33
	v_mul_f32_e32 v16, v16, v17
	v_mul_f32_e32 v17, v23, v19
	v_mul_f32_e32 v17, v17, v18
	v_cvt_pk_bf16_f32 v27, v16, v17
	v_mad_u64_u32 v[16:17], s[20:21], v148, s65, v[114:115]
	v_mov_b32_e32 v18, v17
	v_mad_u64_u32 v[18:19], s[20:21], v149, s65, v[18:19]
	v_mov_b32_e32 v17, v18
	v_lshl_add_u64 v[16:17], v[16:17], 0, v[116:117]
	global_store_dwordx4 v[16:17], v[24:27], off
	v_mul_f32_e32 v16, 0xbfb8aa3b, v153
	v_mul_f32_e32 v17, v153, v153
	v_mul_f32_e32 v12, v12, v16
	v_rcp_f32_e32 v17, v17
	v_exp_f32_e32 v12, v12
	v_mul_f32_e32 v4, v4, v16
	v_exp_f32_e32 v4, v4
	v_fma_f32 v12, v12, v17, v17
	v_rcp_f32_e32 v12, v12
	v_fma_f32 v4, v4, v17, v17
	v_rcp_f32_e32 v4, v4
	v_mul_f32_e32 v8, v8, v12
	v_mul_f32_e32 v12, v13, v16
	v_exp_f32_e32 v12, v12
	v_mul_f32_e32 v0, v0, v4
	v_mul_f32_e32 v4, v5, v16
	v_exp_f32_e32 v4, v4
	v_fma_f32 v12, v12, v17, v17
	v_rcp_f32_e32 v12, v12
	v_fma_f32 v4, v4, v17, v17
	v_rcp_f32_e32 v4, v4
	v_mul_f32_e32 v9, v9, v12
	v_cvt_pk_bf16_f32 v8, v8, v9
	v_mul_f32_e32 v9, v14, v10
	v_mul_f32_e32 v10, v14, v16
	v_exp_f32_e32 v10, v10
	v_mul_f32_e32 v1, v1, v4
	v_fma_f32 v10, v10, v17, v17
	v_rcp_f32_e32 v10, v10
	s_nop 0
	v_mul_f32_e32 v9, v9, v10
	v_mul_f32_e32 v10, v15, v11
	v_mul_f32_e32 v11, v15, v16
	v_exp_f32_e32 v11, v11
	s_nop 0
	v_fma_f32 v11, v11, v17, v17
	v_rcp_f32_e32 v11, v11
	s_nop 0
	v_mul_f32_e32 v10, v10, v11
	v_cvt_pk_bf16_f32 v9, v9, v10
	v_cvt_pk_bf16_f32 v10, v0, v1
	v_mul_f32_e32 v1, v6, v16
	v_mul_f32_e32 v0, v6, v2
	v_exp_f32_e32 v1, v1
	v_mul_f32_e32 v2, v7, v16
	v_exp_f32_e32 v2, v2
	v_fma_f32 v1, v1, v17, v17
	v_rcp_f32_e32 v1, v1
	v_fmac_f32_e32 v17, v2, v17
	v_rcp_f32_e32 v2, v17
	v_mul_f32_e32 v0, v0, v1
	v_mul_f32_e32 v1, v7, v3
	v_mul_f32_e32 v1, v1, v2
	v_cvt_pk_bf16_f32 v11, v0, v1
	v_mad_u64_u32 v[0:1], s[20:21], v146, s65, v[114:115]
	v_mov_b32_e32 v2, v1
	v_mad_u64_u32 v[2:3], s[20:21], v147, s65, v[2:3]
	v_mov_b32_e32 v1, v2
	v_lshl_add_u64 v[0:1], v[0:1], 0, v[116:117]
	s_mov_b64 s[20:21], -1
	global_store_dwordx4 v[0:1], v[8:11], off
	s_cbranch_vccnz .LBB0_64
	s_andn2_b64 vcc, exec, s[6:7]
	s_cbranch_vccnz .LBB0_63
	s_branch .LBB0_63
